# v41 + filter phase 64->2048 layer: the second column tile's weight fragments requested at the top of the ck trip (ahead of the first tile's stores)
# speedup vs baseline: 1.0013x; 1.0013x over previous
; #define GAS __attribute__((address_space(1)))
; #define F3MFMA(a, b, c) __builtin_amdgcn_mfma_f32_16x16x32_bf16(__builtin_bit_cast(bf16x8, (a)), __builtin_bit_cast(bf16x8, (b)), (c), 0, 0, 0)
; __device__ __forceinline__ void filter_phase(Frame& F, int l, bool with_ctx) {
;     ...
;         for (int ck = ck_lo; ck < ck_hi; ++ck) {
; #pragma unroll
;             for (int c2 = 0; c2 < 2; ++c2) { const int ct = 16 * ck + 2 * jg + c2;
;                 const GAS v4u* q = wp + (unsigned)ct * 256u;
;                 const v4u bh0 = q[0], bl0 = q[64], bh1 = q[128], bl1 = q[192];
;                 f32x4 acc[4];
; #pragma unroll
;                 for (int pt = 0; pt < 4; ++pt) { f32x4 a = {0.f, 0.f, 0.f, 0.f};
;                     a = F3MFMA(al[pt][0], bh0, a); a = F3MFMA(ah[pt][0], bl0, a); a = F3MFMA(al[pt][1], bh1, a); a = F3MFMA(ah[pt][1], bl1, a);
;                     a = F3MFMA(ah[pt][0], bh0, a); a = F3MFMA(ah[pt][1], bh1, a); acc[pt] = a; }
;                 const int col = 16 * ct + lq, ch = col & 511;
;                 const float dl = fabsf(HY_MIN_DECAY + (HY_MAX_DECAY - HY_MIN_DECAY) * ((float)ch / 511.0f)) * tsc;
;                 GAS float* dc = dst + (size_t)col * Lq;
; #pragma unroll
;                 for (int pt = 0; pt < 4; ++pt) { const int n = n0 + 16 * pt + 4 * lg; f32x4 v;
; #pragma unroll
;                     for (int r = 0; r < 4; ++r) v[r] = acc[pt][r] * __builtin_amdgcn_exp2f(-(float)(n + r) * dl);
;                     if (!(ct & 32)) *(GAS f32x4*)(dc + n) = v;
;                     else {
; #pragma unroll
;                         for (int r = 0; r < 4; ++r) dc[(Lq - n - r) & (Lq - 1)] = (n + r) == 0 ? 0.f : v[r]; } }
;             }
.LBB0_380:
	v_lshl_add_u64 v[152:153], s[50:51], 4, v[80:81]
	global_load_dwordx4 v[64:67], v[152:153], off
	global_load_dwordx4 v[68:71], v[152:153], off offset:1024
	global_load_dwordx4 v[148:151], v[152:153], off offset:2048
	s_add_i32 s20, s50, 0x100
	s_mov_b32 s21, s51
	v_lshl_add_u64 v[158:159], s[20:21], 4, v[80:81]
	global_load_dwordx4 v[178:181], v[158:159], off
	global_load_dwordx4 v[182:185], v[158:159], off offset:1024
	global_load_dwordx4 v[186:189], v[158:159], off offset:2048
	global_load_dwordx4 v[190:193], v[158:159], off offset:3072
	v_and_b32_e32 v143, 0x1ef, v82
	v_ashrrev_i32_e32 v83, 31, v82
	s_bitcmp1_b32 s3, 5
	s_cselect_b64 s[18:19], -1, 0
	s_mov_b64 s[4:5], -1
	s_waitcnt vmcnt(4)
	v_mfma_f32_16x16x32_bf16 v[72:75], v[4:7], v[64:67], 0
	v_mfma_f32_16x16x32_bf16 v[76:79], v[20:23], v[64:67], 0
	v_mfma_f32_16x16x32_bf16 v[116:119], v[36:39], v[64:67], 0
	v_mfma_f32_16x16x32_bf16 v[144:147], v[52:55], v[64:67], 0
	v_mfma_f32_16x16x32_bf16 v[72:75], v[0:3], v[68:71], v[72:75]
	v_mfma_f32_16x16x32_bf16 v[76:79], v[16:19], v[68:71], v[76:79]
	v_mfma_f32_16x16x32_bf16 v[116:119], v[32:35], v[68:71], v[116:119]
	v_mfma_f32_16x16x32_bf16 v[68:71], v[48:51], v[68:71], v[144:147]
	s_nop 3
	global_load_dwordx4 v[144:147], v[152:153], off offset:3072
	v_mfma_f32_16x16x32_bf16 v[116:119], v[44:47], v[148:151], v[116:119]
	v_mfma_f32_16x16x32_bf16 v[72:75], v[12:15], v[148:151], v[72:75]
	v_mfma_f32_16x16x32_bf16 v[76:79], v[28:31], v[148:151], v[76:79]
	v_mfma_f32_16x16x32_bf16 v[68:71], v[60:63], v[148:151], v[68:71]
	s_waitcnt vmcnt(0)
	v_mfma_f32_16x16x32_bf16 v[152:155], v[40:43], v[144:147], v[116:119]
	s_nop 2
	v_cvt_f32_u32_e32 v118, v143
	v_lshlrev_b64 v[116:117], s22, v[82:83]
	v_lshl_add_u64 v[116:117], v[116:117], 2, s[8:9]
	v_mfma_f32_16x16x32_bf16 v[72:75], v[8:11], v[144:147], v[72:75]
	v_div_scale_f32 v83, s[20:21], s40, s40, v118
	v_rcp_f32_e32 v119, v83
	v_mfma_f32_16x16x32_bf16 v[76:79], v[24:27], v[144:147], v[76:79]
	v_div_scale_f32 v143, vcc, v118, s40, v118
	v_mfma_f32_16x16x32_bf16 v[68:71], v[56:59], v[144:147], v[68:71]
	v_fma_f32 v144, -v83, v119, 1.0
	v_fmac_f32_e32 v119, v144, v119
	v_mul_f32_e32 v156, v143, v119
	v_fma_f32 v144, -v83, v156, v143
	v_fmac_f32_e32 v156, v144, v119
	v_fma_f32 v83, -v83, v156, v143
	v_mfma_f32_16x16x32_bf16 v[72:75], v[0:3], v[64:67], v[72:75]
	v_div_fmas_f32 v83, v83, v119, v156
	s_and_b64 vcc, exec, s[18:19]
	v_mfma_f32_16x16x32_bf16 v[76:79], v[16:19], v[64:67], v[76:79]
	v_mfma_f32_16x16x32_bf16 v[144:147], v[32:35], v[64:67], v[152:155]
	v_mfma_f32_16x16x32_bf16 v[64:67], v[48:51], v[64:67], v[68:71]
	s_nop 2
	v_div_fixup_f32 v68, v83, s40, v118
	v_fmamk_f32 v68, v68, 0x41447cbd, v216
	v_mul_f32_e64 v83, v126, |v68|
	v_mfma_f32_16x16x32_bf16 v[152:155], v[8:11], v[148:151], v[72:75]
	v_mul_f32_e64 v68, v83, -v127
	v_mul_f32_e64 v69, v83, -v128
	v_mul_f32_e64 v118, v83, -v129
	v_mfma_f32_16x16x32_bf16 v[72:75], v[24:27], v[148:151], v[76:79]
	s_nop 2
	v_mul_f32_e64 v79, v83, -v130
	v_exp_f32_e32 v76, v68
	v_exp_f32_e32 v77, v69
	v_exp_f32_e32 v78, v118
	v_exp_f32_e32 v79, v79
	v_mfma_f32_16x16x32_bf16 v[68:71], v[40:43], v[148:151], v[144:147]
	v_mul_f32_e64 v76, v152, v76
	v_mul_f32_e64 v77, v153, v77
	v_pk_mul_f32 v[78:79], v[154:155], v[78:79]
	v_mfma_f32_16x16x32_bf16 v[64:67], v[56:59], v[148:151], v[64:67]
	s_waitcnt vmcnt(0)
	s_cbranch_vccz .LBB0_382
	v_cndmask_b32_e64 v143, v76, 0, s[6:7]
	v_lshl_add_u64 v[118:119], v[176:177], 2, v[116:117]
	global_store_dword v[118:119], v143, off
	v_lshl_add_u64 v[118:119], v[86:87], 2, v[116:117]
	global_store_dword v[118:119], v77, off
	v_lshl_add_u64 v[118:119], v[88:89], 2, v[116:117]
	global_store_dword v[118:119], v78, off
	v_lshl_add_u64 v[118:119], v[90:91], 2, v[116:117]
	s_mov_b64 s[4:5], 0
	global_store_dword v[118:119], v79, off

; #define GAS __attribute__((address_space(1)))
; #define F3MFMA(a, b, c) __builtin_amdgcn_mfma_f32_16x16x32_bf16(__builtin_bit_cast(bf16x8, (a)), __builtin_bit_cast(bf16x8, (b)), (c), 0, 0, 0)
; __device__ __forceinline__ void filter_phase(Frame& F, int l, bool with_ctx) {
;     ...
;             for (int c2 = 0; c2 < 2; ++c2) { const int ct = 16 * ck + 2 * jg + c2;
;                 const GAS v4u* q = wp + (unsigned)ct * 256u;
;                 const v4u bh0 = q[0], bl0 = q[64], bh1 = q[128], bl1 = q[192];
;                 f32x4 acc[4];
; #pragma unroll
;                 for (int pt = 0; pt < 4; ++pt) { f32x4 a = {0.f, 0.f, 0.f, 0.f};
;                     a = F3MFMA(al[pt][0], bh0, a); a = F3MFMA(ah[pt][0], bl0, a); a = F3MFMA(al[pt][1], bh1, a); a = F3MFMA(ah[pt][1], bl1, a);
;                     a = F3MFMA(ah[pt][0], bh0, a); a = F3MFMA(ah[pt][1], bh1, a); acc[pt] = a; }
;                 const int col = 16 * ct + lq, ch = col & 511;
;                 const float dl = fabsf(HY_MIN_DECAY + (HY_MAX_DECAY - HY_MIN_DECAY) * ((float)ch / 511.0f)) * tsc;
;                 GAS float* dc = dst + (size_t)col * Lq;
; #pragma unroll
;                 for (int pt = 0; pt < 4; ++pt) { const int n = n0 + 16 * pt + 4 * lg; f32x4 v;
; #pragma unroll
;                     for (int r = 0; r < 4; ++r) v[r] = acc[pt][r] * __builtin_amdgcn_exp2f(-(float)(n + r) * dl);
;                     if (!(ct & 32)) *(GAS f32x4*)(dc + n) = v;
.LBB0_396:
	s_add_i32 s18, s50, 0x100
	s_mov_b32 s19, s51
	v_lshl_add_u64 v[152:153], s[18:19], 4, v[80:81]
	v_mov_b32_e32 v64, v178
	v_mov_b32_e32 v65, v179
	v_mov_b32_e32 v66, v180
	v_mov_b32_e32 v67, v181
	v_mov_b32_e32 v68, v182
	v_mov_b32_e32 v69, v183
	v_mov_b32_e32 v70, v184
	v_mov_b32_e32 v71, v185
	v_mov_b32_e32 v148, v186
	v_mov_b32_e32 v149, v187
	v_mov_b32_e32 v150, v188
	v_mov_b32_e32 v151, v189
	v_add_u32_e32 v156, 16, v82
	v_and_b32_e32 v83, 0x1ff, v156
	v_cvt_f32_u32_e32 v83, v83
	v_ashrrev_i32_e32 v157, 31, v156
	s_nop 0
	v_mfma_f32_16x16x32_bf16 v[72:75], v[4:7], v[64:67], 0
	v_div_scale_f32 v143, vcc, v83, s40, v83
	v_mfma_f32_16x16x32_bf16 v[76:79], v[20:23], v[64:67], 0
	v_mfma_f32_16x16x32_bf16 v[116:119], v[36:39], v[64:67], 0
	v_mfma_f32_16x16x32_bf16 v[144:147], v[52:55], v[64:67], 0
	s_nop 0
	v_mfma_f32_16x16x32_bf16 v[72:75], v[0:3], v[68:71], v[72:75]
	v_mfma_f32_16x16x32_bf16 v[76:79], v[16:19], v[68:71], v[76:79]
	v_mfma_f32_16x16x32_bf16 v[116:119], v[32:35], v[68:71], v[116:119]
	v_mfma_f32_16x16x32_bf16 v[68:71], v[48:51], v[68:71], v[144:147]
	s_nop 2
	v_mov_b32_e32 v144, v190
	v_mov_b32_e32 v145, v191
	v_mov_b32_e32 v146, v192
	v_mov_b32_e32 v147, v193
	s_nop 0
	v_mfma_f32_16x16x32_bf16 v[116:119], v[44:47], v[148:151], v[116:119]
	v_mfma_f32_16x16x32_bf16 v[72:75], v[12:15], v[148:151], v[72:75]
	v_mfma_f32_16x16x32_bf16 v[76:79], v[28:31], v[148:151], v[76:79]
	v_mfma_f32_16x16x32_bf16 v[68:71], v[60:63], v[148:151], v[68:71]
	s_nop 0
	v_mfma_f32_16x16x32_bf16 v[152:155], v[40:43], v[144:147], v[116:119]
	s_nop 2
	v_div_scale_f32 v118, s[18:19], s40, s40, v83
	v_rcp_f32_e32 v119, v118
	v_mfma_f32_16x16x32_bf16 v[72:75], v[8:11], v[144:147], v[72:75]
	v_lshlrev_b64 v[116:117], s22, v[156:157]
	v_lshl_add_u64 v[116:117], v[116:117], 2, s[8:9]
	s_mov_b64 s[18:19], -1
	v_mfma_f32_16x16x32_bf16 v[76:79], v[24:27], v[144:147], v[76:79]
	v_mfma_f32_16x16x32_bf16 v[68:71], v[56:59], v[144:147], v[68:71]
	v_fma_f32 v144, -v118, v119, 1.0
	v_fmac_f32_e32 v119, v144, v119
	v_mul_f32_e32 v156, v143, v119
	v_fma_f32 v144, -v118, v156, v143
	v_fmac_f32_e32 v156, v144, v119
	v_fma_f32 v118, -v118, v156, v143
	v_mfma_f32_16x16x32_bf16 v[72:75], v[0:3], v[64:67], v[72:75]
	v_div_fmas_f32 v118, v118, v119, v156
	s_and_b64 vcc, exec, s[4:5]
	v_mfma_f32_16x16x32_bf16 v[76:79], v[16:19], v[64:67], v[76:79]
	v_mfma_f32_16x16x32_bf16 v[144:147], v[32:35], v[64:67], v[152:155]
	v_mfma_f32_16x16x32_bf16 v[64:67], v[48:51], v[64:67], v[68:71]
	s_nop 2
	v_div_fixup_f32 v68, v118, s40, v83
	v_fmamk_f32 v68, v68, 0x41447cbd, v216
	v_mul_f32_e64 v83, v126, |v68|
	v_mfma_f32_16x16x32_bf16 v[152:155], v[8:11], v[148:151], v[72:75]
	v_mul_f32_e64 v68, v83, -v127
	v_mul_f32_e64 v69, v83, -v128
	v_mul_f32_e64 v118, v83, -v129
	v_mfma_f32_16x16x32_bf16 v[72:75], v[24:27], v[148:151], v[76:79]
	s_nop 2
	v_mul_f32_e64 v79, v83, -v130
	v_exp_f32_e32 v76, v68
	v_exp_f32_e32 v77, v69
	v_exp_f32_e32 v78, v118
	v_exp_f32_e32 v79, v79
	v_mfma_f32_16x16x32_bf16 v[68:71], v[40:43], v[148:151], v[144:147]
	v_mul_f32_e64 v76, v76, v152
	v_mul_f32_e64 v77, v77, v153
	v_pk_mul_f32 v[78:79], v[78:79], v[154:155]
	v_mfma_f32_16x16x32_bf16 v[64:67], v[56:59], v[148:151], v[64:67]
	s_cbranch_vccnz .LBB0_398
	v_cndmask_b32_e64 v143, v76, 0, s[6:7]
	v_lshl_add_u64 v[118:119], v[176:177], 2, v[116:117]
	global_store_dword v[118:119], v143, off
	v_lshl_add_u64 v[118:119], v[86:87], 2, v[116:117]
	global_store_dword v[118:119], v77, off
	v_lshl_add_u64 v[118:119], v[88:89], 2, v[116:117]
	global_store_dword v[118:119], v78, off
	v_lshl_add_u64 v[118:119], v[90:91], 2, v[116:117]
	s_mov_b64 s[18:19], 0
	global_store_dword v[118:119], v79, off
